# attention softmax: S-m via v_pk_add_f32 (2 elements/instr, negated broadcast), exps 4 at a time, trans-hazard nops gone, same add order
# baseline (speedup 1.0000x reference)
; __device__ __forceinline__ u32x4 pack8(const float (&f)[8]) { u32x4 w; w.x = pk_bf16(f[0], f[1]); w.y = pk_bf16(f[2], f[3]); w.z = pk_bf16(f[4], f[5]); w.w = pk_bf16(f[6], f[7]); return w; }
; #define AT_LDV(buf, hs) do { const LAS unsigned char* vp_ = va + ((((hs) >> 1) >> 1) * 32 + 16 * (((hs) >> 1) & 1)) * AT_VROW + ((hs) & 1) * 128; _Pragma("unroll") for (int d_ = 0; d_ < 2; ++d_) { vf[buf][2 * d_] = vtr(vp_ + d_ * 64); vf[buf][2 * d_ + 1] = vtr(vp_ + 8 * AT_VROW + d_ * 64); } } while (0)
; __device__ __forceinline__ void attn_phase(LAS unsigned char* lds, const bf16* Q, const bf16* KV, const bf16* KPE, const float* rope, bf16* mix, int bid, int G, int tid) {
;     ...
;                 float rs = 0.f;
; #pragma unroll
;                 for (int e = 0; e < 16; ++e) { S0[e] = __builtin_amdgcn_exp2f(S0[e] - mnew); S1[e] = __builtin_amdgcn_exp2f(S1[e] - mnew); rs += S0[e] + S1[e]; }
;                 lrun = lrun * alpha + rs;
;                 if (__builtin_amdgcn_ballot_w64(alpha != 1.0f) != 0ull) {
; #pragma unroll
;                     for (int i = 0; i < 4; ++i)
; #pragma unroll
;                         for (int e = 0; e < 16; ++e) O[i][e] *= alpha; }
; #pragma unroll
;                 for (int hs = 0; hs < 8; ++hs) { const int st = hs >> 1;
;                     if (hs < 7) { AT_LDV((hs + 1) & 1, hs + 1); }
;                     __builtin_amdgcn_sched_barrier(0);
;                     float pf[8];
; #pragma unroll
;                     for (int e = 0; e < 8; ++e) pf[e] = (st >> 1) ? S1[8 * (st & 1) + e] : S0[8 * (st & 1) + e];
;                     const bf16x8 pb = __builtin_bit_cast(bf16x8, pack8(pf));
; #pragma unroll
;                     for (int d_ = 0; d_ < 2; ++d_) { const int dvt = (hs & 1) * 2 + d_; const s16x4 lo = vf[hs & 1][2 * d_], hi = vf[hs & 1][2 * d_ + 1];
;                         const bf16x8 A = (bf16x8){lo[0], lo[1], lo[2], lo[3], hi[0], hi[1], hi[2], hi[3]};
;                         __builtin_amdgcn_s_setprio(1); O[dvt] = __builtin_amdgcn_mfma_f32_32x32x16_bf16(A, pb, O[dvt], 0, 0, 0); __builtin_amdgcn_s_setprio(0); }
;                     __builtin_amdgcn_sched_barrier(0); }
.LBB0_258:
	v_mov_b32_e32 v250, v209
	v_pk_add_f32 v[80:81], v[80:81], v[250:251] op_sel_hi:[1,0] neg_lo:[0,1] neg_hi:[0,1]
	v_pk_add_f32 v[64:65], v[64:65], v[250:251] op_sel_hi:[1,0] neg_lo:[0,1] neg_hi:[0,1]
	v_exp_f32_e32 v80, v80
	v_exp_f32_e32 v210, v64
	v_exp_f32_e32 v81, v81
	v_exp_f32_e32 v211, v65
	v_pk_add_f32 v[82:83], v[82:83], v[250:251] op_sel_hi:[1,0] neg_lo:[0,1] neg_hi:[0,1]
	v_pk_add_f32 v[66:67], v[66:67], v[250:251] op_sel_hi:[1,0] neg_lo:[0,1] neg_hi:[0,1]
	v_add_f32_e32 v242, v80, v210
	v_add_f32_e32 v251, v81, v211
	v_add_f32_e32 v242, v251, v242
	v_exp_f32_e32 v82, v82
	v_exp_f32_e32 v212, v66
	v_exp_f32_e32 v83, v83
	v_exp_f32_e32 v213, v67
	v_pk_add_f32 v[84:85], v[84:85], v[250:251] op_sel_hi:[1,0] neg_lo:[0,1] neg_hi:[0,1]
	v_pk_add_f32 v[68:69], v[68:69], v[250:251] op_sel_hi:[1,0] neg_lo:[0,1] neg_hi:[0,1]
	v_add_f32_e32 v251, v82, v212
	v_add_f32_e32 v242, v251, v242
	v_add_f32_e32 v251, v83, v213
	v_add_f32_e32 v242, v251, v242
	v_exp_f32_e32 v84, v84
	v_exp_f32_e32 v214, v68
	v_exp_f32_e32 v85, v85
	v_exp_f32_e32 v215, v69
	v_pk_add_f32 v[86:87], v[86:87], v[250:251] op_sel_hi:[1,0] neg_lo:[0,1] neg_hi:[0,1]
	v_pk_add_f32 v[70:71], v[70:71], v[250:251] op_sel_hi:[1,0] neg_lo:[0,1] neg_hi:[0,1]
	v_add_f32_e32 v251, v84, v214
	v_add_f32_e32 v242, v251, v242
	v_add_f32_e32 v251, v85, v215
	v_add_f32_e32 v242, v251, v242
	v_exp_f32_e32 v86, v86
	v_exp_f32_e32 v228, v70
	v_exp_f32_e32 v87, v87
	v_exp_f32_e32 v229, v71
	v_pk_add_f32 v[88:89], v[88:89], v[250:251] op_sel_hi:[1,0] neg_lo:[0,1] neg_hi:[0,1]
	v_pk_add_f32 v[72:73], v[72:73], v[250:251] op_sel_hi:[1,0] neg_lo:[0,1] neg_hi:[0,1]
	v_add_f32_e32 v251, v86, v228
	v_add_f32_e32 v242, v251, v242
	v_add_f32_e32 v251, v87, v229
	v_add_f32_e32 v242, v251, v242
	v_exp_f32_e32 v88, v88
	v_exp_f32_e32 v230, v72
	v_exp_f32_e32 v89, v89
	v_exp_f32_e32 v231, v73
	v_pk_add_f32 v[90:91], v[90:91], v[250:251] op_sel_hi:[1,0] neg_lo:[0,1] neg_hi:[0,1]
	v_pk_add_f32 v[74:75], v[74:75], v[250:251] op_sel_hi:[1,0] neg_lo:[0,1] neg_hi:[0,1]
	v_add_f32_e32 v251, v88, v230
	v_add_f32_e32 v242, v251, v242
	v_add_f32_e32 v251, v89, v231
	v_add_f32_e32 v242, v251, v242
	v_exp_f32_e32 v90, v90
	v_exp_f32_e32 v232, v74
	v_exp_f32_e32 v91, v91
	v_exp_f32_e32 v233, v75
	v_pk_add_f32 v[92:93], v[92:93], v[250:251] op_sel_hi:[1,0] neg_lo:[0,1] neg_hi:[0,1]
	v_pk_add_f32 v[76:77], v[76:77], v[250:251] op_sel_hi:[1,0] neg_lo:[0,1] neg_hi:[0,1]
	v_add_f32_e32 v251, v90, v232
	v_add_f32_e32 v242, v251, v242
	v_add_f32_e32 v251, v91, v233
	v_add_f32_e32 v242, v251, v242
	v_exp_f32_e32 v92, v92
	v_exp_f32_e32 v234, v76
	v_exp_f32_e32 v93, v93
	v_exp_f32_e32 v235, v77
	v_pk_add_f32 v[94:95], v[94:95], v[250:251] op_sel_hi:[1,0] neg_lo:[0,1] neg_hi:[0,1]
	v_pk_add_f32 v[78:79], v[78:79], v[250:251] op_sel_hi:[1,0] neg_lo:[0,1] neg_hi:[0,1]
	v_add_f32_e32 v251, v92, v234
	v_add_f32_e32 v242, v251, v242
	v_add_f32_e32 v251, v93, v235
	v_add_f32_e32 v242, v251, v242
	v_exp_f32_e32 v94, v94
	v_exp_f32_e32 v236, v78
	v_exp_f32_e32 v95, v95
	v_exp_f32_e32 v237, v79
	s_nop 0
	v_add_f32_e32 v251, v94, v236
	v_add_f32_e32 v242, v251, v242
	v_add_f32_e32 v251, v95, v237
	v_add_f32_e32 v242, v251, v242
	ds_read_b64_tr_b16 v[64:65], v208 offset:25728
	ds_read_b64_tr_b16 v[66:67], v208 offset:28288
	ds_read_b64_tr_b16 v[68:69], v208 offset:25792
	ds_read_b64_tr_b16 v[70:71], v208 offset:28352
	v_fmac_f32_e32 v242, v207, v184
	v_cvt_pk_bf16_f32 v72, v80, v81
	v_cvt_pk_bf16_f32 v73, v82, v83
	v_cvt_pk_bf16_f32 v74, v84, v85
	v_cvt_pk_bf16_f32 v75, v86, v87
	s_setprio 1
	s_nop 0
	v_mfma_f32_32x32x16_bf16 v[48:63], v[170:173], v[72:75], v[48:63]
	s_setprio 0
	s_setprio 1
	v_mfma_f32_32x32x16_bf16 v[32:47], v[166:169], v[72:75], v[32:47]
	s_setprio 0
	ds_read_b64_tr_b16 v[76:77], v208 offset:30720
	ds_read_b64_tr_b16 v[78:79], v208 offset:33280
	ds_read_b64_tr_b16 v[80:81], v208 offset:30784
	ds_read_b64_tr_b16 v[82:83], v208 offset:33344
	s_setprio 1
	s_waitcnt lgkmcnt(0)
	v_mfma_f32_32x32x16_bf16 v[16:31], v[64:67], v[72:75], v[16:31]
	s_setprio 0
	s_setprio 1
	v_mfma_f32_32x32x16_bf16 v[0:15], v[68:71], v[72:75], v[0:15]
	s_setprio 0
	ds_read_b64_tr_b16 v[64:65], v208 offset:30848
	ds_read_b64_tr_b16 v[66:67], v208 offset:33408
	ds_read_b64_tr_b16 v[68:69], v208 offset:30912
	ds_read_b64_tr_b16 v[70:71], v208 offset:33472
	v_cvt_pk_bf16_f32 v72, v88, v89
	v_cvt_pk_bf16_f32 v73, v90, v91
	v_cvt_pk_bf16_f32 v74, v92, v93
	v_cvt_pk_bf16_f32 v75, v94, v95
	s_setprio 1
	s_nop 0
	v_mfma_f32_32x32x16_bf16 v[48:63], v[76:79], v[72:75], v[48:63]
	s_setprio 0
	s_setprio 1
	v_mfma_f32_32x32x16_bf16 v[32:47], v[80:83], v[72:75], v[32:47]
	s_setprio 0
	ds_read_b64_tr_b16 v[76:77], v208 offset:35840
	ds_read_b64_tr_b16 v[78:79], v208 offset:38400
	ds_read_b64_tr_b16 v[82:83], v208 offset:38464
	ds_read_b64_tr_b16 v[80:81], v208 offset:35904
	s_setprio 1
	s_waitcnt lgkmcnt(0)
	v_mfma_f32_32x32x16_bf16 v[16:31], v[64:67], v[72:75], v[16:31]
	s_setprio 0
	s_setprio 1
	v_mfma_f32_32x32x16_bf16 v[0:15], v[68:71], v[72:75], v[0:15]
	s_setprio 0
	ds_read_b64_tr_b16 v[64:65], v208 offset:35968
	ds_read_b64_tr_b16 v[66:67], v208 offset:38528
	ds_read_b64_tr_b16 v[70:71], v208 offset:38592
	ds_read_b64_tr_b16 v[68:69], v208 offset:36032
	v_cvt_pk_bf16_f32 v72, v210, v211
	v_cvt_pk_bf16_f32 v73, v212, v213
	v_cvt_pk_bf16_f32 v74, v214, v215
	v_cvt_pk_bf16_f32 v75, v228, v229
	s_setprio 1
	s_nop 0
	v_mfma_f32_32x32x16_bf16 v[48:63], v[76:79], v[72:75], v[48:63]
	s_setprio 0
	s_setprio 1
	v_mfma_f32_32x32x16_bf16 v[32:47], v[80:83], v[72:75], v[32:47]
	s_setprio 0
	ds_read_b64_tr_b16 v[76:77], v208 offset:40960
	ds_read_b64_tr_b16 v[78:79], v208 offset:43520
	ds_read_b64_tr_b16 v[82:83], v208 offset:43584
	ds_read_b64_tr_b16 v[80:81], v208 offset:41024
	s_setprio 1
	s_waitcnt lgkmcnt(0)
	v_mfma_f32_32x32x16_bf16 v[16:31], v[64:67], v[72:75], v[16:31]
	s_setprio 0
	s_setprio 1
	v_mfma_f32_32x32x16_bf16 v[0:15], v[68:71], v[72:75], v[0:15]
	s_setprio 0
	ds_read_b64_tr_b16 v[64:65], v208 offset:41088
	ds_read_b64_tr_b16 v[66:67], v208 offset:43648
	ds_read_b64_tr_b16 v[70:71], v208 offset:43712
	ds_read_b64_tr_b16 v[68:69], v208 offset:41152
	v_cvt_pk_bf16_f32 v72, v230, v231
	v_cvt_pk_bf16_f32 v73, v232, v233
	v_cvt_pk_bf16_f32 v74, v234, v235
	v_cvt_pk_bf16_f32 v75, v236, v237
	s_setprio 1
	s_nop 0
	v_mfma_f32_32x32x16_bf16 v[48:63], v[76:79], v[72:75], v[48:63]
	s_setprio 0
	s_setprio 1
	v_mfma_f32_32x32x16_bf16 v[32:47], v[80:83], v[72:75], v[32:47]
	s_setprio 0
	s_setprio 1
	s_waitcnt lgkmcnt(0)
	v_mfma_f32_32x32x16_bf16 v[16:31], v[64:67], v[72:75], v[16:31]
	s_setprio 0
	s_setprio 1
	v_mfma_f32_32x32x16_bf16 v[0:15], v[68:71], v[72:75], v[0:15]
	s_setprio 0
	v_mov_b32_e32 v207, v242
	s_andn2_b64 vcc, exec, s[34:35]
	s_cbranch_vccz .LBB0_260
	s_branch .LBB0_261
